# phase 12: next unit's first fragment reads issued at the top of the SwiGLU epilogue (overlapping its VALU work) instead of at the unit header
# baseline (speedup 1.0000x reference)
; #define PG8_STAGE(bufoff, gbase, voff) do { _Pragma("unroll") for (int _i = 0; _i < 2; ++_i) \
;         __builtin_amdgcn_global_load_lds((const unsigned*)((const char*)(gbase) + (voff)[_i]), (LAS unsigned*)(lds + (bufoff) + ldsw + _i * 8192), 16, 0, 0); } while (0)
; #define PG8_LDA(dst, b, h) do { _Pragma("unroll") for (int m = 0; m < 4; ++m) _Pragma("unroll") for (int k = 0; k < 2; ++k) dst[m][k] = *(const LAS bf16x8*)(lds + PG8_SA(b, h) + aoff + m * 2048 + k * 1024); } while (0)
; #define PG8_LDB(dst, b, h) do { _Pragma("unroll") for (int n = 0; n < 2; ++n) _Pragma("unroll") for (int k = 0; k < 2; ++k) dst[n][k] = *(const LAS bf16x8*)(lds + PG8_SB(b, h) + boff + n * 2048 + k * 1024); } while (0)
; #define PG8_WAIT_V(n) asm volatile("s_waitcnt vmcnt(" #n ")" ::: "memory")
; #define PG8_BAR __builtin_amdgcn_s_barrier()
; #define PG8_SCHED __builtin_amdgcn_sched_barrier(0)
;     ...
;     PG8_STAGE(PG8_SB(0, 0), cB, voffB); PG8_STAGE(PG8_SB(0, 1), cB + hstep, voffB); PG8_STAGE(PG8_SA(0, 0), cA, voffA); PG8_STAGE(PG8_SA(0, 1), cA + hstep, voffA);
;     if (wr == 1) PG8_BAR;
;     PG8_WAIT_V(2); PG8_BAR;
;     PG8_STAGE(PG8_SB(1, 0), cB + kstep, voffB); PG8_STAGE(PG8_SA(1, 0), cA + kstep, voffA); PG8_STAGE(PG8_SB(1, 1), cB + hstep + kstep, voffB);
;     PG8_WAIT_V(6); PG8_BAR;
;     ...
;             PG8_LDB(B0, 0, 0); PG8_LDB(B1, 0, 1); PG8_SCHED; PG8_LDA(At, 0, 0); PG8_STAGE(PG8_SA(1, 1), a1 + hstep, voffA);
.LBB0_4730:
	s_add_u32 s16, s56, 0x4b000000
	s_mov_b64 s[18:19], 0x80
	s_addc_u32 s17, s57, 0
	s_add_i32 m0, s43, 0x18000
	v_lshl_add_u64 v[8:9], v[8:9], 0, s[18:19]
	s_waitcnt vmcnt(2)
	s_barrier
	global_load_lds_dwordx4 v[8:9], off
	v_lshl_add_u64 v[6:7], v[6:7], 0, s[18:19]
	s_add_i32 m0, s43, 0x1a000
	s_add_i32 s58, s43, 0x8000
	global_load_lds_dwordx4 v[6:7], off
	v_lshl_add_u64 v[2:3], v[2:3], 0, s[18:19]
	s_mov_b32 m0, s58
	s_add_i32 s59, s43, 0xa000
	global_load_lds_dwordx4 v[2:3], off
	v_lshl_add_u64 v[2:3], v[4:5], 0, s[18:19]
	s_mov_b32 m0, s59
	s_mov_b64 s[20:21], 0x40080
	global_load_lds_dwordx4 v[2:3], off
	v_lshl_add_u64 v[2:3], v[0:1], 0, s[20:21]
	s_add_i32 m0, s43, 0x1c000
	v_lshl_add_u64 v[4:5], v[2:3], 0, v[128:129]
	global_load_lds_dwordx4 v[4:5], off
	v_lshl_add_u64 v[2:3], v[2:3], 0, v[134:135]
	s_add_i32 m0, s43, 0x1e000
	s_lshl_b32 s3, s3, 5
	global_load_lds_dwordx4 v[2:3], off
	v_lshrrev_b32_e32 v3, 1, v10
	v_and_b32_e32 v3, 24, v3
	v_and_b32_e32 v2, 15, v10
	v_lshlrev_b32_e32 v4, 1, v3
	v_lshl_or_b32 v148, s4, 6, v2
	v_lshl_or_b32 v2, v2, 6, v4
	v_lshlrev_b32_e32 v4, 2, v10
	s_lshl_b32 s4, s4, 13
	v_and_b32_e32 v4, 32, v4
	s_and_b32 s3, s3, 0x60
	v_bitop3_b32 v5, v2, s4, v4 bitop3:0xde
	s_lshl_b32 s4, s3, 7
	v_bitop3_b32 v149, s4, v2, v4 bitop3:0xf6
	v_lshlrev_b32_e32 v2, 14, v12
	v_and_b32_e32 v2, 0xffff8000, v2
	v_or_b32_e32 v150, s3, v3
	v_lshl_add_u32 v2, v13, 11, v2
	v_and_b32_e32 v3, 1, v12
	v_lshl_or_b32 v2, v3, 6, v2
	v_lshl_add_u32 v138, v15, 1, v2
	v_lshlrev_b32_e32 v2, 14, v11
	v_and_b32_e32 v2, 0xffff8000, v2
	s_waitcnt vmcnt(6)
	s_cmpk_lt_u32 s2, 0x100
	v_lshl_add_u32 v2, v14, 11, v2
	v_and_b32_e32 v3, 1, v11
	s_cselect_b64 s[24:25], -1, 0
	v_mov_b32_e32 v139, 0
	v_lshl_or_b32 v2, v3, 6, v2
	s_add_i32 s61, 0, 0x10000
	s_add_i32 s62, 0, 0x14000
	s_ashr_i32 s60, s33, 31
	v_ashrrev_i32_e32 v131, 31, v130
	v_lshl_add_u32 v140, v16, 1, v2
	v_mov_b32_e32 v141, v139
	s_mov_b64 s[26:27], 0x100
	v_add_u32_e32 v151, s61, v149
	v_add_u32_e32 v152, s62, v149
	v_add_u32_e32 v153, 0, v5
	s_mov_b32 s28, 0x3773ad84
	s_mov_b32 s30, 0x3973ad84
	s_mov_b32 s32, 0x4d8d45ca
	s_mov_b32 s63, 0xc3e00000
	s_movk_i32 s64, 0x1c00
	s_mov_b32 s68, 0x1c000
	s_mov_b32 s69, 0
	s_mov_b32 s70, 0x8c000
	s_mov_b32 s71, 0
	v_mov_b32_e32 v154, 0x43e00000
	global_load_dwordx4 v[230:233], v139, s[10:11]
	global_load_dwordx3 v[234:236], v139, s[10:11] offset:16
	s_waitcnt vmcnt(0)
	s_barrier
	ds_read_b128 v[156:159], v151
	ds_read_b128 v[160:163], v151 offset:1024
	ds_read_b128 v[164:167], v151 offset:2048
	ds_read_b128 v[168:171], v151 offset:3072
	ds_read_b128 v[172:175], v152
	ds_read_b128 v[176:179], v152 offset:1024
	ds_read_b128 v[180:183], v152 offset:2048
	ds_read_b128 v[184:187], v152 offset:3072
	ds_read_b128 v[188:191], v153
	ds_read_b128 v[192:195], v153 offset:1024
	ds_read_b128 v[196:199], v153 offset:2048
	ds_read_b128 v[200:203], v153 offset:3072
	ds_read_b128 v[204:207], v153 offset:4096
	ds_read_b128 v[208:211], v153 offset:5120
	ds_read_b128 v[212:215], v153 offset:6144
	ds_read_b128 v[216:219], v153 offset:7168
	s_branch .LBB0_4733

; #define PG8_STAGE(bufoff, gbase, voff) do { _Pragma("unroll") for (int _i = 0; _i < 2; ++_i) \
;         __builtin_amdgcn_global_load_lds((const unsigned*)((const char*)(gbase) + (voff)[_i]), (LAS unsigned*)(lds + (bufoff) + ldsw + _i * 8192), 16, 0, 0); } while (0)
; #define PG8_LDA(dst, b, h) do { _Pragma("unroll") for (int m = 0; m < 4; ++m) _Pragma("unroll") for (int k = 0; k < 2; ++k) dst[m][k] = *(const LAS bf16x8*)(lds + PG8_SA(b, h) + aoff + m * 2048 + k * 1024); } while (0)
; #define PG8_LDB(dst, b, h) do { _Pragma("unroll") for (int n = 0; n < 2; ++n) _Pragma("unroll") for (int k = 0; k < 2; ++k) dst[n][k] = *(const LAS bf16x8*)(lds + PG8_SB(b, h) + boff + n * 2048 + k * 1024); } while (0)
; #define PG8_SCHED __builtin_amdgcn_sched_barrier(0)
; __device__ __forceinline__ u32x4 pack8bf(const f32x4 a, const f32x4 b) { u32x4 w; w.x = cvt_pk_bf16(a[0], a[1]); w.y = cvt_pk_bf16(a[2], a[3]); w.z = cvt_pk_bf16(b[0], b[1]); w.w = cvt_pk_bf16(b[2], b[3]); return w; }
; __device__ __forceinline__ void ln_stats(const float* st, int row, float& mu, float& rs) { const f32x2 s = *(const f32x2*)(st + 2 * (size_t)row); mu = s[0] * (1.0f / DM); rs = 1.0f / sqrtf(s[1] * (1.0f / DM) - mu * mu + LN_EPS); }
;     ...
;             PG8_LDB(B0, 0, 0); PG8_LDB(B1, 0, 1); PG8_SCHED; PG8_LDA(At, 0, 0); PG8_STAGE(PG8_SA(1, 1), a1 + hstep, voffA);
;     __device__ __forceinline__ void operator()(EPI_ARGS) const {
;     ...
;             for (int m = 0; m < 4; ++m) { const int row = row0 + ai * HALF + m * 16; f32x4 r[2];
;                 float mu = 0.f, rs = 1.f; if constexpr (FOLD) ln_stats(st, row, mu, rs);
; #pragma unroll
;                 for (int n = 0; n < 2; ++n) { f32x4 g = acc[ai][0][m][n], up = acc[ai][1][m][n];
;                     if constexpr (!PRE) { g = g * ascale; up = up * ascale; }
;                     if constexpr (FOLD) { g = (g - cg[n] * mu) * rs + dg[n]; up = (up - cu[n] * mu) * rs + du[n]; }
;                     if constexpr (!PRE) up = up * oscale;
; #pragma unroll
;                     for (int j = 0; j < 4; ++j) { const float e = __builtin_amdgcn_exp2f(g[j] * -1.4426950408889634f); r[n][j] = g[j] * __builtin_amdgcn_rcpf(1.0f + e) * up[j]; } }
;                 if constexpr (F8OUT) *(u32x2*)((unsigned char*)O + (size_t)row * ldc + col0) = pack8fp8(r[0], r[1]);
;                 else *(u32x4*)((bf16_t*)O + (size_t)row * ldc + col0) = pack8bf(r[0], r[1]); }
.LBB0_4741:
	ds_read_b128 v[156:159], v151
	ds_read_b128 v[160:163], v151 offset:1024
	ds_read_b128 v[164:167], v151 offset:2048
	ds_read_b128 v[168:171], v151 offset:3072
	ds_read_b128 v[172:175], v152
	ds_read_b128 v[176:179], v152 offset:1024
	ds_read_b128 v[180:183], v152 offset:2048
	ds_read_b128 v[184:187], v152 offset:3072
	ds_read_b128 v[188:191], v153
	ds_read_b128 v[192:195], v153 offset:1024
	ds_read_b128 v[196:199], v153 offset:2048
	ds_read_b128 v[200:203], v153 offset:3072
	ds_read_b128 v[204:207], v153 offset:4096
	ds_read_b128 v[208:211], v153 offset:5120
	ds_read_b128 v[212:215], v153 offset:6144
	ds_read_b128 v[216:219], v153 offset:7168
	v_cvt_f32_i32_e32 v121, v121
	v_cvt_f32_i32_e32 v123, v123
	v_cvt_f32_i32_e32 v122, v122
	v_cvt_f32_i32_e32 v120, v120
	v_cvt_f32_i32_e32 v125, v125
	v_cvt_f32_i32_e32 v124, v124
	v_cvt_f32_i32_e32 v113, v113
	v_cvt_f32_i32_e32 v115, v115
	v_cvt_f32_i32_e32 v114, v114
	v_cvt_f32_i32_e32 v112, v112
	v_cvt_f32_i32_e32 v127, v127
	v_cvt_f32_i32_e32 v126, v126
	v_cvt_f32_i32_e32 v117, v117
	v_cvt_f32_i32_e32 v116, v116
	v_cvt_f32_i32_e32 v105, v105
	v_cvt_f32_i32_e32 v107, v107
	v_cvt_f32_i32_e32 v106, v106
	v_cvt_f32_i32_e32 v104, v104
	v_cvt_f32_i32_e32 v119, v119
	v_cvt_f32_i32_e32 v118, v118
	v_cvt_f32_i32_e32 v109, v109
	v_cvt_f32_i32_e32 v108, v108
	v_cvt_f32_i32_e32 v97, v97
	v_cvt_f32_i32_e32 v99, v99
	v_cvt_f32_i32_e32 v98, v98
	v_cvt_f32_i32_e32 v96, v96
	v_cvt_f32_i32_e32 v93, v93
	v_cvt_f32_i32_e32 v92, v92
	v_cvt_f32_i32_e32 v91, v91
	v_cvt_f32_i32_e32 v90, v90
	v_cvt_f32_i32_e32 v85, v85
	v_cvt_f32_i32_e32 v84, v84
	v_cvt_f32_i32_e32 v83, v83
	v_cvt_f32_i32_e32 v82, v82
	v_cvt_f32_i32_e32 v77, v77
	v_cvt_f32_i32_e32 v76, v76
	v_cvt_f32_i32_e32 v75, v75
	v_cvt_f32_i32_e32 v74, v74
	v_cvt_f32_i32_e32 v111, v111
	v_cvt_f32_i32_e32 v110, v110
	v_cvt_f32_i32_e32 v101, v101
	v_cvt_f32_i32_e32 v100, v100
	v_cvt_f32_i32_e32 v95, v95
	v_cvt_f32_i32_e32 v94, v94
	v_cvt_f32_i32_e32 v89, v89
	v_cvt_f32_i32_e32 v88, v88
	v_cvt_f32_i32_e32 v87, v87
	v_cvt_f32_i32_e32 v86, v86
	v_cvt_f32_i32_e32 v81, v81
	v_cvt_f32_i32_e32 v80, v80
	v_cvt_f32_i32_e32 v79, v79
	v_cvt_f32_i32_e32 v78, v78
	v_cvt_f32_i32_e32 v73, v73
	v_cvt_f32_i32_e32 v72, v72
	v_cvt_f32_i32_e32 v65, v65
	v_cvt_f32_i32_e32 v67, v67
	v_cvt_f32_i32_e32 v66, v66
	v_cvt_f32_i32_e32 v64, v64
	v_cvt_f32_i32_e32 v103, v103
	v_cvt_f32_i32_e32 v102, v102
	v_cvt_f32_i32_e32 v69, v69
	v_cvt_f32_i32_e32 v68, v68
	v_cvt_f32_i32_e32 v57, v57
	v_cvt_f32_i32_e32 v59, v59
	v_cvt_f32_i32_e32 v58, v58
	v_cvt_f32_i32_e32 v56, v56
	v_cvt_f32_i32_e32 v71, v71
	v_cvt_f32_i32_e32 v70, v70
	v_cvt_f32_i32_e32 v61, v61
	v_cvt_f32_i32_e32 v60, v60
	v_cvt_f32_i32_e32 v49, v49
	v_cvt_f32_i32_e32 v51, v51
	v_cvt_f32_i32_e32 v50, v50
	v_cvt_f32_i32_e32 v48, v48
	v_cvt_f32_i32_e32 v63, v63
	v_cvt_f32_i32_e32 v62, v62
	v_cvt_f32_i32_e32 v53, v53
	v_cvt_f32_i32_e32 v52, v52
	v_cvt_f32_i32_e32 v41, v41
	v_cvt_f32_i32_e32 v43, v43
	v_cvt_f32_i32_e32 v42, v42
	v_cvt_f32_i32_e32 v40, v40
	v_cvt_f32_i32_e32 v55, v55
	v_cvt_f32_i32_e32 v54, v54
	v_cvt_f32_i32_e32 v45, v45
	v_cvt_f32_i32_e32 v44, v44
	v_cvt_f32_i32_e32 v33, v33
	v_cvt_f32_i32_e32 v35, v35
	v_cvt_f32_i32_e32 v34, v34
	v_cvt_f32_i32_e32 v32, v32
	v_cvt_f32_i32_e32 v29, v29
	v_cvt_f32_i32_e32 v28, v28
	v_cvt_f32_i32_e32 v27, v27
	v_cvt_f32_i32_e32 v26, v26
	v_cvt_f32_i32_e32 v21, v21
	v_cvt_f32_i32_e32 v20, v20
	v_cvt_f32_i32_e32 v19, v19
	v_cvt_f32_i32_e32 v18, v18
	v_cvt_f32_i32_e32 v13, v13
	v_cvt_f32_i32_e32 v12, v12
	v_cvt_f32_i32_e32 v9, v9
	v_cvt_f32_i32_e32 v8, v8
	v_cvt_f32_i32_e32 v5, v5
	v_cvt_f32_i32_e32 v4, v4
	v_cvt_f32_i32_e32 v1, v1
	v_cvt_f32_i32_e32 v0, v0
	v_cvt_f32_i32_e32 v47, v47
	v_cvt_f32_i32_e32 v46, v46
	v_cvt_f32_i32_e32 v37, v37
	v_cvt_f32_i32_e32 v36, v36
	v_cvt_f32_i32_e32 v31, v31
	v_cvt_f32_i32_e32 v30, v30
	v_cvt_f32_i32_e32 v25, v25
	v_cvt_f32_i32_e32 v24, v24
	v_cvt_f32_i32_e32 v23, v23
	v_cvt_f32_i32_e32 v22, v22
	v_cvt_f32_i32_e32 v17, v17
	v_cvt_f32_i32_e32 v16, v16
	v_cvt_f32_i32_e32 v15, v15
	v_cvt_f32_i32_e32 v14, v14
	v_mul_f32_e32 v146, 0xb7afc6c0, v124
	v_exp_f32_e32 v147, v146
	v_mul_f32_e32 v146, 0xb7afc6c0, v125
	v_cvt_f32_i32_e32 v39, v39
	v_cvt_f32_i32_e32 v38, v38
	v_exp_f32_e32 v144, v146
	v_fma_f32 v147, v147, s32, s32
	v_rcp_f32_e32 v145, v147
	v_fma_f32 v147, v144, s32, s32
	v_rcp_f32_e32 v144, v147
	v_mul_f32_e32 v145, v124, v145
	v_mul_f32_e32 v124, 0xb7afc6c0, v126
	v_exp_f32_e32 v124, v124
	v_mul_f32_e32 v144, v125, v144
	v_mul_f32_e32 v125, 0xb7afc6c0, v127
	v_exp_f32_e32 v125, v125
	v_mul_f32_e32 v145, v92, v145
	v_fma_f32 v124, v124, s32, s32
	v_mul_f32_e32 v92, 0xb7afc6c0, v120
	v_rcp_f32_e32 v124, v124
	v_fma_f32 v125, v125, s32, s32
	v_exp_f32_e32 v92, v92
	v_rcp_f32_e32 v125, v125
	v_mul_f32_e32 v126, v126, v124
	v_mul_f32_e32 v144, v93, v144
	v_fma_f32 v124, v92, s32, s32
	v_mul_f32_e32 v127, v127, v125
	v_rcp_f32_e32 v124, v124
	v_mul_f32_e32 v125, 0xb7afc6c0, v121
	v_exp_f32_e32 v125, v125
	v_med3_f32 v145, v145, s63, v154
	v_mul_f32_e32 v120, v120, v124
	v_mul_f32_e32 v88, v88, v120
	v_fma_f32 v120, v125, s32, s32
	v_mul_f32_e32 v124, 0xb7afc6c0, v122
	v_rcp_f32_e32 v120, v120
	v_exp_f32_e32 v124, v124
	v_mul_f32_e32 v125, 0xb7afc6c0, v123
	v_exp_f32_e32 v125, v125
	v_mul_f32_e32 v120, v121, v120
	v_fma_f32 v121, v124, s32, s32
	v_rcp_f32_e32 v121, v121
	v_fma_f32 v124, v125, s32, s32
	v_rcp_f32_e32 v124, v124
	v_med3_f32 v144, v144, s63, v154
	v_mul_f32_e32 v122, v122, v121
	v_mul_f32_e32 v122, v90, v122
	v_mul_f32_e32 v90, v123, v124
	v_mul_f32_e32 v123, v91, v90
	v_cvt_pk_fp8_f32 v90, v145, v144
	v_mul_f32_e32 v89, v89, v120
; __device__ __forceinline__ u32x4 pack8bf(const f32x4 a, const f32x4 b) { u32x4 w; w.x = cvt_pk_bf16(a[0], a[1]); w.y = cvt_pk_bf16(a[2], a[3]); w.z = cvt_pk_bf16(b[0], b[1]); w.w = cvt_pk_bf16(b[2], b[3]); return w; }
; __device__ __forceinline__ void ln_stats(const float* st, int row, float& mu, float& rs) { const f32x2 s = *(const f32x2*)(st + 2 * (size_t)row); mu = s[0] * (1.0f / DM); rs = 1.0f / sqrtf(s[1] * (1.0f / DM) - mu * mu + LN_EPS); }
;     __device__ __forceinline__ void operator()(EPI_ARGS) const {
;     ...
;             for (int m = 0; m < 4; ++m) { const int row = row0 + ai * HALF + m * 16; f32x4 r[2];
;                 float mu = 0.f, rs = 1.f; if constexpr (FOLD) ln_stats(st, row, mu, rs);
; #pragma unroll
;                 for (int n = 0; n < 2; ++n) { f32x4 g = acc[ai][0][m][n], up = acc[ai][1][m][n];
;                     if constexpr (!PRE) { g = g * ascale; up = up * ascale; }
;                     if constexpr (FOLD) { g = (g - cg[n] * mu) * rs + dg[n]; up = (up - cu[n] * mu) * rs + du[n]; }
;                     if constexpr (!PRE) up = up * oscale;
; #pragma unroll
;                     for (int j = 0; j < 4; ++j) { const float e = __builtin_amdgcn_exp2f(g[j] * -1.4426950408889634f); r[n][j] = g[j] * __builtin_amdgcn_rcpf(1.0f + e) * up[j]; } }
;                 if constexpr (F8OUT) *(u32x2*)((unsigned char*)O + (size_t)row * ldc + col0) = pack8fp8(r[0], r[1]);
;                 else *(u32x4*)((bf16_t*)O + (size_t)row * ldc + col0) = pack8bf(r[0], r[1]); }
	v_mul_f32_e32 v126, v94, v126
	v_mul_f32_e32 v127, v95, v127
	v_med3_f32 v88, v88, s63, v154
	v_med3_f32 v89, v89, s63, v154
	v_med3_f32 v144, v126, s63, v154
	v_med3_f32 v145, v127, s63, v154
	v_cvt_pk_fp8_f32 v91, v88, v89
	v_cvt_pk_fp8_f32 v90, v144, v145 op_sel:[0,0,1]
	v_med3_f32 v144, v122, s63, v154
	v_mul_f32_e32 v122, 0xb7afc6c0, v116
	v_med3_f32 v145, v123, s63, v154
	v_exp_f32_e32 v122, v122
	v_mul_f32_e32 v123, 0xb7afc6c0, v117
	v_exp_f32_e32 v123, v123
	v_cvt_pk_fp8_f32 v91, v144, v145 op_sel:[0,0,1]
	v_lshl_add_u32 v249, s44, 8, v148
	v_lshl_or_b32 v146, s42, 7, v150
	v_mov_b64_e32 v[144:145], s[16:17]
	v_ashrrev_i32_e32 v147, 31, v146
	v_mad_i64_i32 v[88:89], s[4:5], v249, s64, v[144:145]
	v_fma_f32 v122, v122, s32, s32
	v_lshl_add_u64 v[250:251], v[88:89], 0, v[146:147]
	v_rcp_f32_e32 v122, v122
	v_fma_f32 v123, v123, s32, s32
	v_rcp_f32_e32 v123, v123
	global_store_dwordx2 v[250:251], v[90:91], off
	v_mul_f32_e32 v91, 0xb7afc6c0, v118
	v_exp_f32_e32 v91, v91
	v_mul_f32_e32 v88, 0xb7afc6c0, v119
	v_exp_f32_e32 v88, v88
	v_mul_f32_e32 v90, v116, v122
	v_mul_f32_e32 v84, v84, v90
	v_mul_f32_e32 v90, v117, v123
	v_mul_f32_e32 v85, v85, v90
	v_fma_f32 v90, v91, s32, s32
	v_rcp_f32_e32 v90, v90
	v_fma_f32 v91, v88, s32, s32
	v_mul_f32_e32 v88, 0xb7afc6c0, v112
	v_rcp_f32_e32 v91, v91
	v_exp_f32_e32 v88, v88
	v_mul_f32_e32 v90, v118, v90
	v_mul_f32_e32 v86, v86, v90
	v_mul_f32_e32 v90, v119, v91
	v_fma_f32 v91, v88, s32, s32
	v_rcp_f32_e32 v91, v91
	v_mul_f32_e32 v88, 0xb7afc6c0, v113
	v_exp_f32_e32 v88, v88
	v_mul_f32_e32 v87, v87, v90
	v_mul_f32_e32 v90, v112, v91
	v_mul_f32_e32 v91, 0xb7afc6c0, v114
	v_mul_f32_e32 v80, v80, v90
	v_fma_f32 v90, v88, s32, s32
	v_exp_f32_e32 v91, v91
	v_mul_f32_e32 v88, 0xb7afc6c0, v115
	v_exp_f32_e32 v88, v88
	v_rcp_f32_e32 v90, v90
	v_fma_f32 v91, v91, s32, s32
	v_rcp_f32_e32 v91, v91
	v_fma_f32 v88, v88, s32, s32
	v_rcp_f32_e32 v88, v88
	v_mul_f32_e32 v90, v113, v90
	v_mul_f32_e32 v81, v81, v90
	v_mul_f32_e32 v90, v114, v91
	v_mul_f32_e32 v90, v82, v90
	v_mul_f32_e32 v82, v115, v88
	v_mul_f32_e32 v91, v83, v82
	v_med3_f32 v83, v84, s63, v154
	v_med3_f32 v84, v85, s63, v154
	v_cvt_pk_fp8_f32 v82, v83, v84
	v_med3_f32 v80, v80, s63, v154
	v_med3_f32 v81, v81, s63, v154
	v_med3_f32 v86, v86, s63, v154
	v_med3_f32 v87, v87, s63, v154
	v_cvt_pk_fp8_f32 v83, v80, v81
	v_cvt_pk_fp8_f32 v82, v86, v87 op_sel:[0,0,1]
	v_mul_f32_e32 v86, 0xb7afc6c0, v108
	v_exp_f32_e32 v86, v86
	v_mul_f32_e32 v87, 0xb7afc6c0, v109
	v_med3_f32 v80, v90, s63, v154
	v_med3_f32 v81, v91, s63, v154
	v_exp_f32_e32 v87, v87
	v_cvt_pk_fp8_f32 v83, v80, v81 op_sel:[0,0,1]
	v_fma_f32 v86, v86, s32, s32
	v_lshl_add_u64 v[250:251], v[250:251], 0, s[68:69]
	v_rcp_f32_e32 v86, v86
	v_fma_f32 v87, v87, s32, s32
	v_rcp_f32_e32 v87, v87
	global_store_dwordx2 v[250:251], v[82:83], off
	v_mul_f32_e32 v83, 0xb7afc6c0, v110
	v_exp_f32_e32 v83, v83
	v_mul_f32_e32 v80, 0xb7afc6c0, v111
	v_exp_f32_e32 v80, v80
	v_mul_f32_e32 v82, v108, v86
	v_mul_f32_e32 v76, v76, v82
	v_mul_f32_e32 v82, v109, v87
	v_mul_f32_e32 v77, v77, v82
	v_fma_f32 v82, v83, s32, s32
	v_rcp_f32_e32 v82, v82
	v_fma_f32 v83, v80, s32, s32
	v_mul_f32_e32 v80, 0xb7afc6c0, v104
	v_rcp_f32_e32 v83, v83
	v_exp_f32_e32 v80, v80
	v_mul_f32_e32 v82, v110, v82
	v_mul_f32_e32 v78, v78, v82
	v_mul_f32_e32 v82, v111, v83
	v_fma_f32 v83, v80, s32, s32
	v_rcp_f32_e32 v83, v83
	v_mul_f32_e32 v80, 0xb7afc6c0, v105
	v_exp_f32_e32 v80, v80
	v_mul_f32_e32 v79, v79, v82
	v_mul_f32_e32 v82, v104, v83
	v_mul_f32_e32 v83, 0xb7afc6c0, v106
	v_mul_f32_e32 v72, v72, v82
	v_fma_f32 v82, v80, s32, s32
	v_exp_f32_e32 v83, v83
	v_mul_f32_e32 v80, 0xb7afc6c0, v107
	v_exp_f32_e32 v80, v80
	v_rcp_f32_e32 v82, v82
	v_fma_f32 v83, v83, s32, s32
	v_rcp_f32_e32 v83, v83
	v_fma_f32 v80, v80, s32, s32
	v_rcp_f32_e32 v80, v80
	v_mul_f32_e32 v82, v105, v82
	v_mul_f32_e32 v73, v73, v82
	v_mul_f32_e32 v82, v106, v83
	v_mul_f32_e32 v82, v74, v82
	v_mul_f32_e32 v74, v107, v80
	v_mul_f32_e32 v83, v75, v74
	v_med3_f32 v75, v76, s63, v154
	v_med3_f32 v76, v77, s63, v154
	v_cvt_pk_fp8_f32 v74, v75, v76
	v_med3_f32 v72, v72, s63, v154
	v_med3_f32 v73, v73, s63, v154
	v_med3_f32 v78, v78, s63, v154
	v_med3_f32 v79, v79, s63, v154
	v_cvt_pk_fp8_f32 v75, v72, v73
	v_cvt_pk_fp8_f32 v74, v78, v79 op_sel:[0,0,1]
	v_mul_f32_e32 v78, 0xb7afc6c0, v100
	v_exp_f32_e32 v78, v78
	v_mul_f32_e32 v79, 0xb7afc6c0, v101
	v_med3_f32 v72, v82, s63, v154
	v_med3_f32 v73, v83, s63, v154
	v_exp_f32_e32 v79, v79
	v_cvt_pk_fp8_f32 v75, v72, v73 op_sel:[0,0,1]
	v_fma_f32 v78, v78, s32, s32
	v_lshl_add_u64 v[250:251], v[250:251], 0, s[68:69]
	v_rcp_f32_e32 v78, v78
	v_fma_f32 v79, v79, s32, s32
	v_rcp_f32_e32 v79, v79
	global_store_dwordx2 v[250:251], v[74:75], off
	v_mul_f32_e32 v75, 0xb7afc6c0, v102
	v_exp_f32_e32 v75, v75
	v_mul_f32_e32 v72, 0xb7afc6c0, v103
	v_exp_f32_e32 v72, v72
	v_mul_f32_e32 v74, v100, v78
	v_mul_f32_e32 v68, v68, v74
	v_mul_f32_e32 v74, v101, v79
	v_mul_f32_e32 v69, v69, v74
	v_fma_f32 v74, v75, s32, s32
	v_rcp_f32_e32 v74, v74
	v_fma_f32 v75, v72, s32, s32
	v_mul_f32_e32 v72, 0xb7afc6c0, v96
	v_rcp_f32_e32 v75, v75
	v_exp_f32_e32 v72, v72
	v_mul_f32_e32 v74, v102, v74
	v_mul_f32_e32 v70, v70, v74
	v_mul_f32_e32 v74, v103, v75
	v_fma_f32 v75, v72, s32, s32
	v_rcp_f32_e32 v75, v75
	v_mul_f32_e32 v72, 0xb7afc6c0, v97
	v_exp_f32_e32 v72, v72
	v_mul_f32_e32 v71, v71, v74
	v_mul_f32_e32 v74, v96, v75
	v_mul_f32_e32 v75, 0xb7afc6c0, v98
	v_mul_f32_e32 v64, v64, v74
	v_fma_f32 v74, v72, s32, s32
	v_exp_f32_e32 v75, v75
	v_mul_f32_e32 v72, 0xb7afc6c0, v99
	v_exp_f32_e32 v72, v72
	v_rcp_f32_e32 v74, v74
	v_fma_f32 v75, v75, s32, s32
; __device__ __forceinline__ u32x4 pack8bf(const f32x4 a, const f32x4 b) { u32x4 w; w.x = cvt_pk_bf16(a[0], a[1]); w.y = cvt_pk_bf16(a[2], a[3]); w.z = cvt_pk_bf16(b[0], b[1]); w.w = cvt_pk_bf16(b[2], b[3]); return w; }
; __device__ __forceinline__ void ln_stats(const float* st, int row, float& mu, float& rs) { const f32x2 s = *(const f32x2*)(st + 2 * (size_t)row); mu = s[0] * (1.0f / DM); rs = 1.0f / sqrtf(s[1] * (1.0f / DM) - mu * mu + LN_EPS); }
;     __device__ __forceinline__ void operator()(EPI_ARGS) const {
;     ...
;             for (int m = 0; m < 4; ++m) { const int row = row0 + ai * HALF + m * 16; f32x4 r[2];
;                 float mu = 0.f, rs = 1.f; if constexpr (FOLD) ln_stats(st, row, mu, rs);
; #pragma unroll
;                 for (int n = 0; n < 2; ++n) { f32x4 g = acc[ai][0][m][n], up = acc[ai][1][m][n];
;                     if constexpr (!PRE) { g = g * ascale; up = up * ascale; }
;                     if constexpr (FOLD) { g = (g - cg[n] * mu) * rs + dg[n]; up = (up - cu[n] * mu) * rs + du[n]; }
;                     if constexpr (!PRE) up = up * oscale;
; #pragma unroll
;                     for (int j = 0; j < 4; ++j) { const float e = __builtin_amdgcn_exp2f(g[j] * -1.4426950408889634f); r[n][j] = g[j] * __builtin_amdgcn_rcpf(1.0f + e) * up[j]; } }
;                 if constexpr (F8OUT) *(u32x2*)((unsigned char*)O + (size_t)row * ldc + col0) = pack8fp8(r[0], r[1]);
;                 else *(u32x4*)((bf16_t*)O + (size_t)row * ldc + col0) = pack8bf(r[0], r[1]); }
	v_rcp_f32_e32 v75, v75
	v_fma_f32 v72, v72, s32, s32
	v_rcp_f32_e32 v72, v72
	v_mul_f32_e32 v74, v97, v74
	v_mul_f32_e32 v65, v65, v74
	v_mul_f32_e32 v74, v98, v75
	v_mul_f32_e32 v74, v66, v74
	v_mul_f32_e32 v66, v99, v72
	v_mul_f32_e32 v75, v67, v66
	v_med3_f32 v67, v68, s63, v154
	v_med3_f32 v68, v69, s63, v154
	v_cvt_pk_fp8_f32 v66, v67, v68
	v_med3_f32 v64, v64, s63, v154
	v_med3_f32 v65, v65, s63, v154
	v_cvt_pk_fp8_f32 v67, v64, v65
	v_med3_f32 v70, v70, s63, v154
	v_med3_f32 v71, v71, s63, v154
	v_cvt_pk_fp8_f32 v66, v70, v71 op_sel:[0,0,1]
	v_med3_f32 v64, v74, s63, v154
	v_med3_f32 v65, v75, s63, v154
	v_mul_f32_e32 v70, 0xb7afc6c0, v60
	v_cvt_pk_fp8_f32 v67, v64, v65 op_sel:[0,0,1]
	v_exp_f32_e32 v70, v70
	v_mul_f32_e32 v71, 0xb7afc6c0, v61
	v_exp_f32_e32 v71, v71
	v_lshl_add_u64 v[250:251], v[250:251], 0, s[68:69]
	global_store_dwordx2 v[250:251], v[66:67], off
	v_fma_f32 v66, v70, s32, s32
	v_rcp_f32_e32 v66, v66
	v_fma_f32 v67, v71, s32, s32
	v_rcp_f32_e32 v67, v67
	v_mul_f32_e32 v60, v60, v66
	v_mul_f32_e32 v66, 0xb7afc6c0, v62
	v_mul_f32_e32 v61, v61, v67
	v_exp_f32_e32 v66, v66
	v_mul_f32_e32 v67, 0xb7afc6c0, v63
	v_exp_f32_e32 v67, v67
	v_mul_f32_e32 v65, 0xb7afc6c0, v56
	v_fma_f32 v66, v66, s32, s32
	v_rcp_f32_e32 v66, v66
	v_fma_f32 v67, v67, s32, s32
	v_exp_f32_e32 v65, v65
	v_rcp_f32_e32 v67, v67
	v_mul_f32_e32 v62, v62, v66
	v_mul_f32_e32 v60, v28, v60
	v_fma_f32 v66, v65, s32, s32
	v_mul_f32_e32 v63, v63, v67
	v_rcp_f32_e32 v66, v66
	v_mul_f32_e32 v67, 0xb7afc6c0, v57
	v_exp_f32_e32 v67, v67
	v_mul_f32_e32 v61, v29, v61
	v_mul_f32_e32 v56, v56, v66
	v_mul_f32_e32 v24, v24, v56
	v_fma_f32 v56, v67, s32, s32
	v_mul_f32_e32 v66, 0xb7afc6c0, v58
	v_rcp_f32_e32 v56, v56
	v_exp_f32_e32 v66, v66
	v_mul_f32_e32 v67, 0xb7afc6c0, v59
	v_exp_f32_e32 v67, v67
	v_mul_f32_e32 v56, v57, v56
	v_fma_f32 v57, v66, s32, s32
	v_rcp_f32_e32 v57, v57
	v_fma_f32 v66, v67, s32, s32
	v_rcp_f32_e32 v66, v66
	v_mul_f32_e32 v25, v25, v56
	v_mul_f32_e32 v58, v58, v57
	v_mul_f32_e32 v58, v26, v58
	v_mul_f32_e32 v26, v59, v66
	v_mul_f32_e32 v59, v27, v26
	v_med3_f32 v27, v60, s63, v154
	v_med3_f32 v56, v61, s63, v154
	v_cvt_pk_fp8_f32 v26, v27, v56
	v_med3_f32 v24, v24, s63, v154
	v_med3_f32 v25, v25, s63, v154
	v_cvt_pk_fp8_f32 v27, v24, v25
	v_med3_f32 v24, v58, s63, v154
	v_mul_f32_e32 v58, 0xb7afc6c0, v52
	v_mul_f32_e32 v62, v30, v62
	v_mul_f32_e32 v63, v31, v63
	v_med3_f32 v25, v59, s63, v154
	v_exp_f32_e32 v58, v58
	v_mul_f32_e32 v59, 0xb7afc6c0, v53
	v_med3_f32 v56, v62, s63, v154
	v_med3_f32 v57, v63, s63, v154
	v_exp_f32_e32 v59, v59
	v_cvt_pk_fp8_f32 v26, v56, v57 op_sel:[0,0,1]
	v_cvt_pk_fp8_f32 v27, v24, v25 op_sel:[0,0,1]
	v_fma_f32 v58, v58, s32, s32
	v_lshl_add_u64 v[250:251], v[250:251], 0, s[70:71]
	v_rcp_f32_e32 v58, v58
	v_fma_f32 v59, v59, s32, s32
	v_rcp_f32_e32 v59, v59
	global_store_dwordx2 v[250:251], v[26:27], off
	v_mul_f32_e32 v27, 0xb7afc6c0, v54
	v_exp_f32_e32 v27, v27
	v_mul_f32_e32 v24, 0xb7afc6c0, v55
	v_exp_f32_e32 v24, v24
	v_mul_f32_e32 v26, v52, v58
	v_mul_f32_e32 v20, v20, v26
	v_mul_f32_e32 v26, v53, v59
	v_mul_f32_e32 v21, v21, v26
	v_fma_f32 v26, v27, s32, s32
	v_rcp_f32_e32 v26, v26
	v_fma_f32 v27, v24, s32, s32
	v_mul_f32_e32 v24, 0xb7afc6c0, v48
	v_rcp_f32_e32 v27, v27
	v_exp_f32_e32 v24, v24
	v_mul_f32_e32 v26, v54, v26
	v_mul_f32_e32 v22, v22, v26
	v_mul_f32_e32 v26, v55, v27
	v_fma_f32 v27, v24, s32, s32
	v_rcp_f32_e32 v27, v27
	v_mul_f32_e32 v24, 0xb7afc6c0, v49
	v_exp_f32_e32 v24, v24
	v_mul_f32_e32 v23, v23, v26
	v_mul_f32_e32 v26, v48, v27
	v_mul_f32_e32 v27, 0xb7afc6c0, v50
	v_mul_f32_e32 v16, v16, v26
	v_fma_f32 v26, v24, s32, s32
	v_exp_f32_e32 v27, v27
	v_mul_f32_e32 v24, 0xb7afc6c0, v51
	v_exp_f32_e32 v24, v24
	v_rcp_f32_e32 v26, v26
	v_fma_f32 v27, v27, s32, s32
	v_rcp_f32_e32 v27, v27
	v_fma_f32 v24, v24, s32, s32
	v_rcp_f32_e32 v24, v24
	v_mul_f32_e32 v26, v49, v26
	v_mul_f32_e32 v17, v17, v26
	v_mul_f32_e32 v26, v50, v27
	v_mul_f32_e32 v26, v18, v26
	v_mul_f32_e32 v18, v51, v24
	v_mul_f32_e32 v27, v19, v18
	v_med3_f32 v19, v20, s63, v154
	v_med3_f32 v20, v21, s63, v154
	v_cvt_pk_fp8_f32 v18, v19, v20
	v_med3_f32 v16, v16, s63, v154
	v_med3_f32 v17, v17, s63, v154
	v_med3_f32 v22, v22, s63, v154
	v_med3_f32 v23, v23, s63, v154
	v_cvt_pk_fp8_f32 v19, v16, v17
; #define PG8_BAR __builtin_amdgcn_s_barrier()
; __device__ __forceinline__ u32x4 pack8bf(const f32x4 a, const f32x4 b) { u32x4 w; w.x = cvt_pk_bf16(a[0], a[1]); w.y = cvt_pk_bf16(a[2], a[3]); w.z = cvt_pk_bf16(b[0], b[1]); w.w = cvt_pk_bf16(b[2], b[3]); return w; }
; __device__ __forceinline__ void ln_stats(const float* st, int row, float& mu, float& rs) { const f32x2 s = *(const f32x2*)(st + 2 * (size_t)row); mu = s[0] * (1.0f / DM); rs = 1.0f / sqrtf(s[1] * (1.0f / DM) - mu * mu + LN_EPS); }
;     ...
;         if (!has_next) break;
; #pragma unroll
;         for (int a = 0; a < 2; ++a)
; #pragma unroll
;             for (int b = 0; b < 2; ++b)
; #pragma unroll
;                 for (int m = 0; m < 4; ++m)
; #pragma unroll
;                     for (int n = 0; n < 2; ++n) acc[a][b][m][n] = (f32x4){0.f, 0.f, 0.f, 0.f};
;         cur = nxt; cA = nA; cB = nB; ++ui;
;         if (wr == 1) PG8_BAR;
;     __device__ __forceinline__ void operator()(EPI_ARGS) const {
;     ...
;             for (int m = 0; m < 4; ++m) { const int row = row0 + ai * HALF + m * 16; f32x4 r[2];
;                 float mu = 0.f, rs = 1.f; if constexpr (FOLD) ln_stats(st, row, mu, rs);
; #pragma unroll
;                 for (int n = 0; n < 2; ++n) { f32x4 g = acc[ai][0][m][n], up = acc[ai][1][m][n];
;                     if constexpr (!PRE) { g = g * ascale; up = up * ascale; }
;                     if constexpr (FOLD) { g = (g - cg[n] * mu) * rs + dg[n]; up = (up - cu[n] * mu) * rs + du[n]; }
;                     if constexpr (!PRE) up = up * oscale;
; #pragma unroll
;                     for (int j = 0; j < 4; ++j) { const float e = __builtin_amdgcn_exp2f(g[j] * -1.4426950408889634f); r[n][j] = g[j] * __builtin_amdgcn_rcpf(1.0f + e) * up[j]; } }
;                 if constexpr (F8OUT) *(u32x2*)((unsigned char*)O + (size_t)row * ldc + col0) = pack8fp8(r[0], r[1]);
;                 else *(u32x4*)((bf16_t*)O + (size_t)row * ldc + col0) = pack8bf(r[0], r[1]); }
	v_cvt_pk_fp8_f32 v18, v22, v23 op_sel:[0,0,1]
	v_mul_f32_e32 v22, 0xb7afc6c0, v44
	v_exp_f32_e32 v22, v22
	v_mul_f32_e32 v23, 0xb7afc6c0, v45
	v_med3_f32 v16, v26, s63, v154
	v_med3_f32 v17, v27, s63, v154
	v_exp_f32_e32 v23, v23
	v_cvt_pk_fp8_f32 v19, v16, v17 op_sel:[0,0,1]
	v_fma_f32 v22, v22, s32, s32
	v_lshl_add_u64 v[250:251], v[250:251], 0, s[68:69]
	v_rcp_f32_e32 v22, v22
	v_fma_f32 v23, v23, s32, s32
	v_rcp_f32_e32 v23, v23
	global_store_dwordx2 v[250:251], v[18:19], off
	v_mul_f32_e32 v19, 0xb7afc6c0, v46
	v_exp_f32_e32 v19, v19
	v_mul_f32_e32 v16, 0xb7afc6c0, v47
	v_exp_f32_e32 v16, v16
	v_mul_f32_e32 v18, v44, v22
	v_mul_f32_e32 v12, v12, v18
	v_mul_f32_e32 v18, v45, v23
	v_mul_f32_e32 v13, v13, v18
	v_fma_f32 v18, v19, s32, s32
	v_rcp_f32_e32 v18, v18
	v_fma_f32 v19, v16, s32, s32
	v_mul_f32_e32 v16, 0xb7afc6c0, v40
	v_rcp_f32_e32 v19, v19
	v_exp_f32_e32 v16, v16
	v_mul_f32_e32 v18, v46, v18
	v_mul_f32_e32 v14, v14, v18
	v_mul_f32_e32 v18, v47, v19
	v_fma_f32 v19, v16, s32, s32
	v_rcp_f32_e32 v19, v19
	v_mul_f32_e32 v16, 0xb7afc6c0, v41
	v_exp_f32_e32 v16, v16
	v_mul_f32_e32 v15, v15, v18
	v_mul_f32_e32 v18, v40, v19
	v_mul_f32_e32 v19, 0xb7afc6c0, v42
	v_mul_f32_e32 v8, v8, v18
	v_fma_f32 v18, v16, s32, s32
	v_exp_f32_e32 v19, v19
	v_mul_f32_e32 v16, 0xb7afc6c0, v43
	v_exp_f32_e32 v16, v16
	v_rcp_f32_e32 v18, v18
	v_fma_f32 v19, v19, s32, s32
	v_cvt_f32_i32_e32 v11, v11
	v_cvt_f32_i32_e32 v10, v10
	v_rcp_f32_e32 v19, v19
	v_fma_f32 v16, v16, s32, s32
	v_rcp_f32_e32 v16, v16
	v_mul_f32_e32 v18, v41, v18
	v_mul_f32_e32 v9, v9, v18
	v_mul_f32_e32 v18, v42, v19
	v_mul_f32_e32 v18, v10, v18
	v_mul_f32_e32 v10, v43, v16
	v_mul_f32_e32 v19, v11, v10
	v_med3_f32 v11, v12, s63, v154
	v_med3_f32 v12, v13, s63, v154
	v_cvt_pk_fp8_f32 v10, v11, v12
	v_med3_f32 v8, v8, s63, v154
	v_med3_f32 v9, v9, s63, v154
	v_med3_f32 v14, v14, s63, v154
	v_med3_f32 v15, v15, s63, v154
	v_cvt_pk_fp8_f32 v11, v8, v9
	v_cvt_pk_fp8_f32 v10, v14, v15 op_sel:[0,0,1]
	v_mul_f32_e32 v14, 0xb7afc6c0, v36
	v_exp_f32_e32 v14, v14
	v_mul_f32_e32 v15, 0xb7afc6c0, v37
	v_med3_f32 v8, v18, s63, v154
	v_med3_f32 v9, v19, s63, v154
	v_exp_f32_e32 v15, v15
	v_cvt_pk_fp8_f32 v11, v8, v9 op_sel:[0,0,1]
	v_fma_f32 v14, v14, s32, s32
	v_lshl_add_u64 v[250:251], v[250:251], 0, s[68:69]
	v_rcp_f32_e32 v14, v14
	v_fma_f32 v15, v15, s32, s32
	v_rcp_f32_e32 v15, v15
	global_store_dwordx2 v[250:251], v[10:11], off
	v_mul_f32_e32 v11, 0xb7afc6c0, v38
	v_exp_f32_e32 v11, v11
	v_mul_f32_e32 v8, 0xb7afc6c0, v39
	v_exp_f32_e32 v8, v8
	v_mul_f32_e32 v10, v36, v14
	v_mul_f32_e32 v4, v4, v10
	v_mul_f32_e32 v10, v37, v15
	v_mul_f32_e32 v5, v5, v10
	v_fma_f32 v10, v11, s32, s32
	v_cvt_f32_i32_e32 v7, v7
	v_cvt_f32_i32_e32 v6, v6
	v_rcp_f32_e32 v10, v10
	v_fma_f32 v11, v8, s32, s32
	v_mul_f32_e32 v8, 0xb7afc6c0, v32
	v_rcp_f32_e32 v11, v11
	v_exp_f32_e32 v8, v8
	v_mul_f32_e32 v10, v38, v10
	v_mul_f32_e32 v6, v6, v10
	v_mul_f32_e32 v10, v39, v11
	v_fma_f32 v11, v8, s32, s32
	v_rcp_f32_e32 v11, v11
	v_mul_f32_e32 v8, 0xb7afc6c0, v33
	v_exp_f32_e32 v8, v8
	v_mul_f32_e32 v7, v7, v10
	v_mul_f32_e32 v10, v32, v11
	v_mul_f32_e32 v11, 0xb7afc6c0, v34
	v_mul_f32_e32 v0, v0, v10
	v_fma_f32 v10, v8, s32, s32
	v_exp_f32_e32 v11, v11
	v_mul_f32_e32 v8, 0xb7afc6c0, v35
	v_exp_f32_e32 v8, v8
	v_rcp_f32_e32 v10, v10
	v_fma_f32 v11, v11, s32, s32
	v_cvt_f32_i32_e32 v3, v3
	v_cvt_f32_i32_e32 v2, v2
	v_rcp_f32_e32 v11, v11
	v_fma_f32 v8, v8, s32, s32
	v_rcp_f32_e32 v8, v8
	v_mul_f32_e32 v10, v33, v10
	v_mul_f32_e32 v1, v1, v10
	v_mul_f32_e32 v10, v34, v11
	v_mul_f32_e32 v10, v2, v10
	v_mul_f32_e32 v2, v35, v8
	v_mul_f32_e32 v11, v3, v2
	v_med3_f32 v3, v4, s63, v154
	v_med3_f32 v4, v5, s63, v154
	v_cvt_pk_fp8_f32 v2, v3, v4
	v_med3_f32 v0, v0, s63, v154
	v_med3_f32 v1, v1, s63, v154
	v_cvt_pk_fp8_f32 v3, v0, v1
	v_med3_f32 v6, v6, s63, v154
	v_med3_f32 v7, v7, s63, v154
	v_med3_f32 v0, v10, s63, v154
	v_med3_f32 v1, v11, s63, v154
	v_cvt_pk_fp8_f32 v2, v6, v7 op_sel:[0,0,1]
	v_cvt_pk_fp8_f32 v3, v0, v1 op_sel:[0,0,1]
	v_lshl_add_u64 v[0:1], v[250:251], 0, s[68:69]
	s_and_b64 vcc, exec, s[2:3]
	s_mov_b64 s[2:3], -1
	global_store_dwordx2 v[0:1], v[2:3], off
	s_cbranch_vccnz .LBB0_4732
	s_andn2_b64 vcc, exec, s[14:15]
	s_cbranch_vccnz .LBB0_4731
	s_barrier
	s_branch .LBB0_4731
